# rwkv_out: all staging loads of a unit (RHO/Y0/V rows, prev-V row, chunk state, gate-lora rows) issued in one batch before the unit barrier; single wait ladder
# baseline (speedup 1.0000x reference)
; __device__ __forceinline__ int opaque_bid() { int b = blockIdx.x; asm volatile("" : "+s"(b)); return b; }
; __device__ __forceinline__ unsigned pk2(float lo, float hi) { unsigned r; asm("v_cvt_pk_bf16_f32 %0, %1, %2" : "=v"(r) : "v"(lo), "v"(hi)); return r; }
; __device__ __forceinline__ void rwkv_out_phase(const bf16* Z, const RwkvW w, const bf16* Wl, const float* Ub, const bf16* RHO, const bf16* Y0, const float* BON, bf16* MIX, unsigned char* lds) {
;     ...
;     for (int u = opaque_bid() ^ 8; u < 2048; u += gridDim.x) {
;         const int bh = u >> 7, c = u & 127, b = bh >> 3, h = bh & 7, col0 = h * 64; const size_t rowbase = (size_t)b * SEQ + c * 128;
;         __syncthreads();
;         for (int ci = tid; ci < 1024; ci += NTHR) { const int j = ci >> 3, c8 = (ci & 7) * 8;
;             *(u32x4*)(Rs + j * 72 + c8) = *(const u32x4*)(RHO + (rowbase + j) * 512 + col0 + c8);
;             *(u32x4*)(Ys + j * 72 + c8) = *(const u32x4*)(Y0 + (rowbase + j) * 512 + col0 + c8);
;             *(u32x4*)(Vs + (j + 1) * 72 + c8) = *(const u32x4*)(Z + (rowbase + j) * EVEN_IN + 3072 + col0 + c8); }
;         if (tid < 8) { u32x4 pv = {0u, 0u, 0u, 0u}; if (c > 0) pv = *(const u32x4*)(Z + (rowbase - 1) * EVEN_IN + 3072 + col0 + tid * 8); *(u32x4*)(Vs + tid * 8) = pv; }
;         for (int i4 = tid; i4 < 1024; i4 += NTHR) { const int i = i4 >> 4, k4 = (i4 & 15) * 4; f32x4 sv = {0.f, 0.f, 0.f, 0.f};
;             if ((c >> SLOG) > 0) sv = *(const f32x4*)(Ub + (size_t)(bh * NCHK + (c >> SLOG) - 1) * 4096 + i * 64 + k4);
;             *(u32x2*)(Ss + i * 72 + k4) = (u32x2){pk2(sv[0], sv[1]), pk2(sv[2], sv[3])}; }
;         for (int ci = tid; ci < 2048; ci += NTHR) { const int j = ci >> 4, c8 = (ci & 15) * 8; const bf16* zc = Z + (rowbase + j) * EVEN_IN + 3712 + c8;
;             const u32x4 cg = *(const u32x4*)zc; u32x4 pg = {0u, 0u, 0u, 0u}; if (c > 0 || j > 0) pg = *(const u32x4*)(zc - EVEN_IN);
;             const f32x4 m0 = *(const f32x4*)(w.mu + 1664 + c8), m1 = *(const f32x4*)(w.mu + 1668 + c8); u32x4 og;
.LBB0_642:
	s_ashr_i32 s16, s26, 10
	s_ashr_i32 s40, s26, 7
	s_and_b32 s39, s26, 0x7f
	s_ashr_i32 s17, s16, 31
	s_and_b32 s38, s40, 7
	s_lshl_b64 s[16:17], s[16:17], 14
	s_lshl_b32 s18, s39, 7
	s_lshl_b32 s37, s38, 6
	s_or_b32 s16, s16, s18
	s_and_saveexec_b64 s[18:19], s[0:1]
	v_readlane_b32 s41, v240, 50
	s_movk_i32 s54, 0x1ff
	s_mov_b32 s61, s25
	s_lshl_b32 s60, s37, 1
	v_mov_b32_e32 v138, 0
	v_mov_b32_e32 v139, 0
	v_mov_b32_e32 v140, 0
	v_mov_b32_e32 v141, 0
	s_cmp_eq_u32 s39, 0
	s_cbranch_scc1 .Lrw_b_skip
	s_mul_i32 s20, s17, 0x1e00
	s_mul_hi_u32 s21, s16, 0x1e00
	s_add_i32 s21, s21, s20
	s_mul_i32 s20, s16, 0x1e00
	s_add_u32 s20, s94, s20
	s_addc_u32 s21, s95, s21
	s_lshl_b32 s22, s37, 1
	s_add_u32 s20, s20, s22
	s_addc_u32 s21, s21, 0
	s_and_saveexec_b64 s[24:25], s[2:3]
	v_lshl_add_u64 v[2:3], v[50:51], 1, s[20:21]
	global_load_dwordx4 v[138:141], v[2:3], off offset:-1536
	s_or_b64 exec, exec, s[24:25]
.Lrw_b_skip:
	s_cmp_gt_u32 s39, 7
	s_cselect_b64 s[20:21], -1, 0
	s_lshr_b32 s22, s39, 3
	s_lshl_b32 s23, s40, 4
	s_or_b32 s22, s22, s23
	s_add_i32 s22, s22, -1
	s_ashr_i32 s23, s22, 31
	s_lshl_b64 s[22:23], s[22:23], 14
	s_add_u32 s22, s27, s22
	s_addc_u32 s23, s28, s23
	v_ashrrev_i32_e32 v8, 4, v72
	v_and_b32_e32 v9, 60, v100
	v_mov_b32_e32 v142, 0
	v_mov_b32_e32 v143, 0
	v_mov_b32_e32 v144, 0
	v_mov_b32_e32 v145, 0
	v_mov_b32_e32 v148, 0
	v_mov_b32_e32 v149, 0
	v_mov_b32_e32 v150, 0
	v_mov_b32_e32 v151, 0
	s_and_b64 vcc, exec, s[20:21]
	s_cbranch_vccz .Lrw_c_nost
	v_lshlrev_b32_e32 v10, 6, v8
	v_ashrrev_i32_e32 v11, 31, v10
	v_lshl_add_u64 v[10:11], v[10:11], 2, s[22:23]
	v_lshlrev_b32_e32 v0, 2, v9
	s_mov_b64 s[24:25], 0x2000
	v_lshl_add_u64 v[10:11], v[10:11], 0, v[0:1]
	global_load_dwordx4 v[142:145], v[10:11], off
	v_lshl_add_u64 v[12:13], v[10:11], 0, s[24:25]
	global_load_dwordx4 v[148:151], v[12:13], off
.Lrw_c_nost:
	v_mul_lo_u32 v0, v8, s64
	v_lshlrev_b32_e32 v6, 1, v9
	v_add3_u32 v152, 0, v0, v6
	s_lshl_b32 s22, s37, 1
	s_add_u32 s20, s31, s22
	s_addc_u32 s21, s34, 0
	s_add_u32 s22, s29, s22
	s_addc_u32 s23, s30, 0
	v_ashrrev_i32_e32 v8, 3, v72
	v_ashrrev_i32_e32 v9, 31, v8
	v_lshl_add_u64 v[10:11], s[16:17], 0, v[8:9]
	v_lshlrev_b64 v[12:13], 10, v[10:11]
	v_lshlrev_b32_e32 v0, 1, v50
	v_lshl_add_u64 v[4:5], s[20:21], 0, v[12:13]
	v_and_b32_e32 v0, 0x70, v0
	v_lshl_add_u64 v[4:5], v[4:5], 0, v[0:1]
	s_mov_b64 s[24:25], 0x10000
	global_load_dwordx4 v[114:117], v[4:5], off
	v_lshl_add_u64 v[6:7], v[4:5], 0, s[24:25]
	global_load_dwordx4 v[118:121], v[6:7], off
	v_lshl_add_u64 v[4:5], s[22:23], 0, v[12:13]
	v_lshl_add_u64 v[4:5], v[4:5], 0, v[0:1]
	global_load_dwordx4 v[122:125], v[4:5], off
	v_lshl_add_u64 v[6:7], v[4:5], 0, s[24:25]
	global_load_dwordx4 v[126:129], v[6:7], off
	v_mov_b64_e32 v[4:5], s[94:95]
	v_mad_u64_u32 v[4:5], s[42:43], v10, s65, v[4:5]
	v_mov_b32_e32 v6, v5
	v_mad_u64_u32 v[6:7], s[42:43], v11, s65, v[6:7]
	v_mov_b32_e32 v5, v6
	v_lshl_add_u64 v[4:5], v[4:5], 0, s[60:61]
	v_lshl_add_u64 v[4:5], v[4:5], 0, v[0:1]
	v_add_co_u32_e32 v4, vcc, 0x1000, v4
	s_mov_b64 s[24:25], 0x78000
	s_nop 0
	v_addc_co_u32_e32 v5, vcc, 0, v5, vcc
	global_load_dwordx4 v[130:133], v[4:5], off offset:2048
	v_lshl_add_u64 v[6:7], v[4:5], 0, s[24:25]
	global_load_dwordx4 v[134:137], v[6:7], off offset:2048
	v_mul_lo_u32 v8, v8, s64
	v_add3_u32 v158, 0, v8, v0
	v_add3_u32 v160, s41, v8, v0
	v_add_u32_e32 v159, 0x2400, v158
	v_add_u32_e32 v161, 0x2400, v160
	s_cmp_lg_u32 s39, 0
	s_cselect_b64 s[22:23], -1, 0
	v_ashrrev_i32_e32 v10, 4, v72
	v_ashrrev_i32_e32 v11, 31, v10
	v_lshl_add_u64 v[2:3], s[16:17], 0, v[10:11]
	v_mov_b64_e32 v[4:5], s[94:95]
	v_mad_u64_u32 v[4:5], s[24:25], v2, s65, v[4:5]
	v_mov_b32_e32 v0, v5
	v_and_b32_e32 v16, 0x78, v50
	v_mad_u64_u32 v[2:3], s[24:25], v3, s65, v[0:1]
	v_mov_b32_e32 v5, v2
	v_lshlrev_b32_e32 v0, 1, v16
	v_lshl_add_u64 v[12:13], v[4:5], 0, v[0:1]
	v_lshlrev_b32_e32 v11, 2, v16
	global_load_dwordx4 v[206:209], v11, s[14:15]
	global_load_dwordx4 v[210:213], v11, s[14:15] offset:16
	v_add_co_u32_e32 v2, vcc, 0x1000, v12
	s_mov_b64 s[20:21], 0x3c000
	s_nop 0
	v_addc_co_u32_e32 v3, vcc, 0, v13, vcc
	v_mov_b32_e32 v190, 0
	v_mov_b32_e32 v191, 0
	v_mov_b32_e32 v192, 0
	v_mov_b32_e32 v193, 0
	v_add_co_u32_e32 v24, vcc, 0xfffff000, v2
	s_nop 1
	v_addc_co_u32_e32 v25, vcc, -1, v3, vcc
	global_load_dwordx4 v[174:177], v[2:3], off offset:3328
	v_cmp_lt_i32_e32 vcc, 0, v10
	s_or_b64 s[40:41], s[22:23], vcc
	s_and_saveexec_b64 s[24:25], s[40:41]
	global_load_dwordx4 v[190:193], v[24:25], off offset:-256
	s_or_b64 exec, exec, s[24:25]
	v_lshl_add_u64 v[2:3], v[2:3], 0, s[20:21]
	v_lshl_add_u64 v[24:25], v[24:25], 0, s[20:21]
	global_load_dwordx4 v[178:181], v[2:3], off offset:3328
	global_load_dwordx4 v[194:197], v[24:25], off offset:-256
	v_lshl_add_u64 v[2:3], v[2:3], 0, s[20:21]
	v_lshl_add_u64 v[24:25], v[24:25], 0, s[20:21]
	global_load_dwordx4 v[182:185], v[2:3], off offset:3328
	global_load_dwordx4 v[198:201], v[24:25], off offset:-256
	v_lshl_add_u64 v[2:3], v[2:3], 0, s[20:21]
	v_lshl_add_u64 v[24:25], v[24:25], 0, s[20:21]
	global_load_dwordx4 v[186:189], v[2:3], off offset:3328
	global_load_dwordx4 v[202:205], v[24:25], off offset:-256
	v_mul_lo_u32 v10, v10, s88
	v_add3_u32 v153, 0, v10, v0
	s_mov_b32 s42, 0x10000
	s_mov_b32 s43, 0x14000
	s_barrier
; __device__ __forceinline__ unsigned pk2(float lo, float hi) { unsigned r; asm("v_cvt_pk_bf16_f32 %0, %1, %2" : "=v"(r) : "v"(lo), "v"(hi)); return r; }
; __device__ __forceinline__ float sigmoidf_(float x) { return __builtin_amdgcn_rcpf(1.f + __builtin_amdgcn_exp2f(x * -1.4426950408889634f)); }
; __device__ __forceinline__ void rwkv_out_phase(const bf16* Z, const RwkvW w, const bf16* Wl, const float* Ub, const bf16* RHO, const bf16* Y0, const float* BON, bf16* MIX, unsigned char* lds) {
;     ...
;         for (int ci = tid; ci < 1024; ci += NTHR) { const int j = ci >> 3, c8 = (ci & 7) * 8;
;             *(u32x4*)(Rs + j * 72 + c8) = *(const u32x4*)(RHO + (rowbase + j) * 512 + col0 + c8);
;             *(u32x4*)(Ys + j * 72 + c8) = *(const u32x4*)(Y0 + (rowbase + j) * 512 + col0 + c8);
;             *(u32x4*)(Vs + (j + 1) * 72 + c8) = *(const u32x4*)(Z + (rowbase + j) * EVEN_IN + 3072 + col0 + c8); }
;         if (tid < 8) { u32x4 pv = {0u, 0u, 0u, 0u}; if (c > 0) pv = *(const u32x4*)(Z + (rowbase - 1) * EVEN_IN + 3072 + col0 + tid * 8); *(u32x4*)(Vs + tid * 8) = pv; }
;         for (int i4 = tid; i4 < 1024; i4 += NTHR) { const int i = i4 >> 4, k4 = (i4 & 15) * 4; f32x4 sv = {0.f, 0.f, 0.f, 0.f};
;             if ((c >> SLOG) > 0) sv = *(const f32x4*)(Ub + (size_t)(bh * NCHK + (c >> SLOG) - 1) * 4096 + i * 64 + k4);
;             *(u32x2*)(Ss + i * 72 + k4) = (u32x2){pk2(sv[0], sv[1]), pk2(sv[2], sv[3])}; }
;         for (int ci = tid; ci < 2048; ci += NTHR) { const int j = ci >> 4, c8 = (ci & 15) * 8; const bf16* zc = Z + (rowbase + j) * EVEN_IN + 3712 + c8;
;             const u32x4 cg = *(const u32x4*)zc; u32x4 pg = {0u, 0u, 0u, 0u}; if (c > 0 || j > 0) pg = *(const u32x4*)(zc - EVEN_IN);
;             const f32x4 m0 = *(const f32x4*)(w.mu + 1664 + c8), m1 = *(const f32x4*)(w.mu + 1668 + c8); u32x4 og;
; #pragma unroll
;             for (int x = 0; x < 4; ++x) { const float c0 = __uint_as_float(cg[x] << 16), c1 = __uint_as_float(cg[x] & 0xffff0000u), p0 = __uint_as_float(pg[x] << 16), p1 = __uint_as_float(pg[x] & 0xffff0000u);
;                 const float ma = x < 2 ? m0[2 * x] : m1[2 * x - 4], mb = x < 2 ? m0[2 * x + 1] : m1[2 * x - 3];
;                 og[x] = pk2(sigmoidf_(c0 + ma * (p0 - c0)), sigmoidf_(c1 + mb * (p1 - c1))); }
;             *(u32x4*)(AG + j * 136 + c8) = og; }
	s_waitcnt vmcnt(15)
	ds_write_b128 v158, v[114:117]
	s_waitcnt vmcnt(14)
	ds_write_b128 v159, v[118:121]
	s_waitcnt vmcnt(13)
	ds_write_b128 v158, v[122:125] offset:62464
	s_waitcnt vmcnt(12)
	ds_write_b128 v159, v[126:129] offset:62464
	s_waitcnt vmcnt(11)
	ds_write_b128 v160, v[130:133] offset:144
	s_waitcnt vmcnt(10)
	ds_write_b128 v161, v[134:137] offset:144
	s_and_saveexec_b64 s[24:25], s[2:3]
	ds_write_b128 v101, v[138:141]
	s_or_b64 exec, exec, s[24:25]
	v_cvt_pk_bf16_f32 v142, v142, v143
	v_cvt_pk_bf16_f32 v143, v144, v145
	v_cvt_pk_bf16_f32 v148, v148, v149
	v_cvt_pk_bf16_f32 v149, v150, v151
	ds_write_b64 v152, v[142:143] offset:18432
	ds_write_b64 v152, v[148:149] offset:23040
	s_waitcnt vmcnt(6)
	v_lshlrev_b32_e32 v11, 16, v190
	v_lshlrev_b32_e32 v12, 16, v174
	v_and_b32_e32 v174, 0xffff0000, v174
	v_and_b32_e32 v190, 0xffff0000, v190
	v_lshlrev_b32_e32 v13, 16, v191
	v_lshlrev_b32_e32 v24, 16, v175
	v_and_b32_e32 v175, 0xffff0000, v175
	v_and_b32_e32 v191, 0xffff0000, v191
	v_lshlrev_b32_e32 v15, 16, v192
	v_lshlrev_b32_e32 v26, 16, v176
	v_and_b32_e32 v176, 0xffff0000, v176
	v_and_b32_e32 v192, 0xffff0000, v192
	v_lshlrev_b32_e32 v25, 16, v193
	v_lshlrev_b32_e32 v28, 16, v177
	v_and_b32_e32 v177, 0xffff0000, v177
	v_and_b32_e32 v193, 0xffff0000, v193
	v_sub_f32_e32 v190, v190, v174
	v_sub_f32_e32 v11, v11, v12
	v_sub_f32_e32 v191, v191, v175
	v_sub_f32_e32 v13, v13, v24
	v_sub_f32_e32 v192, v192, v176
	v_sub_f32_e32 v15, v15, v26
	v_sub_f32_e32 v193, v193, v177
	v_sub_f32_e32 v25, v25, v28
	v_fmac_f32_e32 v174, v207, v190
	v_fmac_f32_e32 v12, v206, v11
	v_fmac_f32_e32 v175, v209, v191
	v_fmac_f32_e32 v24, v208, v13
	v_fmac_f32_e32 v176, v211, v192
	v_fmac_f32_e32 v26, v210, v15
	v_fmac_f32_e32 v177, v213, v193
	v_fmac_f32_e32 v28, v212, v25
	v_mul_f32_e32 v174, 0xbfb8aa3b, v174
	v_mul_f32_e32 v175, 0xbfb8aa3b, v175
	v_mul_f32_e32 v176, 0xbfb8aa3b, v176
	v_mul_f32_e32 v177, 0xbfb8aa3b, v177
	v_mul_f32_e32 v12, 0xbfb8aa3b, v12
	v_mul_f32_e32 v24, 0xbfb8aa3b, v24
	v_mul_f32_e32 v26, 0xbfb8aa3b, v26
	v_mul_f32_e32 v28, 0xbfb8aa3b, v28
	v_exp_f32_e32 v174, v174
	v_exp_f32_e32 v175, v175
	v_exp_f32_e32 v176, v176
	v_exp_f32_e32 v177, v177
	v_exp_f32_e32 v12, v12
	v_exp_f32_e32 v24, v24
	v_exp_f32_e32 v26, v26
	v_exp_f32_e32 v28, v28
	v_add_f32_e32 v174, 1.0, v174
	v_add_f32_e32 v175, 1.0, v175
	v_add_f32_e32 v176, 1.0, v176
	v_add_f32_e32 v177, 1.0, v177
	v_add_f32_e32 v12, 1.0, v12
	v_add_f32_e32 v24, 1.0, v24
	v_add_f32_e32 v26, 1.0, v26
	v_add_f32_e32 v28, 1.0, v28
	v_rcp_f32_e32 v174, v174
	v_rcp_f32_e32 v175, v175
	v_rcp_f32_e32 v176, v176
	v_rcp_f32_e32 v177, v177
	v_rcp_f32_e32 v12, v12
	v_rcp_f32_e32 v24, v24
	v_rcp_f32_e32 v26, v26
	v_rcp_f32_e32 v28, v28
	s_nop 0
	v_cvt_pk_bf16_f32 v174, v12, v174
	v_cvt_pk_bf16_f32 v175, v24, v175
	v_cvt_pk_bf16_f32 v176, v26, v176
	v_cvt_pk_bf16_f32 v177, v28, v177
	ds_write_b128 v153, v[174:177] offset:27648
	s_waitcnt vmcnt(4)
	v_lshlrev_b32_e32 v11, 16, v194
	v_lshlrev_b32_e32 v12, 16, v178
	v_and_b32_e32 v178, 0xffff0000, v178
	v_and_b32_e32 v194, 0xffff0000, v194
	v_lshlrev_b32_e32 v13, 16, v195
	v_lshlrev_b32_e32 v24, 16, v179
	v_and_b32_e32 v179, 0xffff0000, v179
	v_and_b32_e32 v195, 0xffff0000, v195
	v_lshlrev_b32_e32 v15, 16, v196
	v_lshlrev_b32_e32 v26, 16, v180
	v_and_b32_e32 v180, 0xffff0000, v180
	v_and_b32_e32 v196, 0xffff0000, v196
	v_lshlrev_b32_e32 v25, 16, v197
	v_lshlrev_b32_e32 v28, 16, v181
	v_and_b32_e32 v181, 0xffff0000, v181
	v_and_b32_e32 v197, 0xffff0000, v197
	v_sub_f32_e32 v194, v194, v178
	v_sub_f32_e32 v11, v11, v12
	v_sub_f32_e32 v195, v195, v179
	v_sub_f32_e32 v13, v13, v24
	v_sub_f32_e32 v196, v196, v180
	v_sub_f32_e32 v15, v15, v26
	v_sub_f32_e32 v197, v197, v181
	v_sub_f32_e32 v25, v25, v28
	v_fmac_f32_e32 v178, v207, v194
	v_fmac_f32_e32 v12, v206, v11
	v_fmac_f32_e32 v179, v209, v195
	v_fmac_f32_e32 v24, v208, v13
	v_fmac_f32_e32 v180, v211, v196
	v_fmac_f32_e32 v26, v210, v15
	v_fmac_f32_e32 v181, v213, v197
	v_fmac_f32_e32 v28, v212, v25
	v_mul_f32_e32 v178, 0xbfb8aa3b, v178
	v_mul_f32_e32 v179, 0xbfb8aa3b, v179
	v_mul_f32_e32 v180, 0xbfb8aa3b, v180
	v_mul_f32_e32 v181, 0xbfb8aa3b, v181
	v_mul_f32_e32 v12, 0xbfb8aa3b, v12
	v_mul_f32_e32 v24, 0xbfb8aa3b, v24
	v_mul_f32_e32 v26, 0xbfb8aa3b, v26
	v_mul_f32_e32 v28, 0xbfb8aa3b, v28
	v_exp_f32_e32 v178, v178
	v_exp_f32_e32 v179, v179
	v_exp_f32_e32 v180, v180
	v_exp_f32_e32 v181, v181
	v_exp_f32_e32 v12, v12
	v_exp_f32_e32 v24, v24
	v_exp_f32_e32 v26, v26
	v_exp_f32_e32 v28, v28
	v_add_f32_e32 v178, 1.0, v178
	v_add_f32_e32 v179, 1.0, v179
	v_add_f32_e32 v180, 1.0, v180
	v_add_f32_e32 v181, 1.0, v181
	v_add_f32_e32 v12, 1.0, v12
	v_add_f32_e32 v24, 1.0, v24
	v_add_f32_e32 v26, 1.0, v26
	v_add_f32_e32 v28, 1.0, v28
	v_rcp_f32_e32 v178, v178
	v_rcp_f32_e32 v179, v179
	v_rcp_f32_e32 v180, v180
	v_rcp_f32_e32 v181, v181
	v_rcp_f32_e32 v12, v12
	v_rcp_f32_e32 v24, v24
	v_rcp_f32_e32 v26, v26
	v_rcp_f32_e32 v28, v28
	s_nop 0
	v_cvt_pk_bf16_f32 v178, v12, v178
	v_cvt_pk_bf16_f32 v179, v24, v179
	v_cvt_pk_bf16_f32 v180, v26, v180
	v_cvt_pk_bf16_f32 v181, v28, v181
	ds_write_b128 v153, v[178:181] offset:36352
	s_waitcnt vmcnt(2)
; __device__ __forceinline__ unsigned pk2(float lo, float hi) { unsigned r; asm("v_cvt_pk_bf16_f32 %0, %1, %2" : "=v"(r) : "v"(lo), "v"(hi)); return r; }
; __device__ __forceinline__ float sigmoidf_(float x) { return __builtin_amdgcn_rcpf(1.f + __builtin_amdgcn_exp2f(x * -1.4426950408889634f)); }
; __device__ __forceinline__ void rwkv_out_phase(const bf16* Z, const RwkvW w, const bf16* Wl, const float* Ub, const bf16* RHO, const bf16* Y0, const float* BON, bf16* MIX, unsigned char* lds) {
;     ...
;         for (int ci = tid; ci < 2048; ci += NTHR) { const int j = ci >> 4, c8 = (ci & 15) * 8; const bf16* zc = Z + (rowbase + j) * EVEN_IN + 3712 + c8;
;             const u32x4 cg = *(const u32x4*)zc; u32x4 pg = {0u, 0u, 0u, 0u}; if (c > 0 || j > 0) pg = *(const u32x4*)(zc - EVEN_IN);
;             const f32x4 m0 = *(const f32x4*)(w.mu + 1664 + c8), m1 = *(const f32x4*)(w.mu + 1668 + c8); u32x4 og;
; #pragma unroll
;             for (int x = 0; x < 4; ++x) { const float c0 = __uint_as_float(cg[x] << 16), c1 = __uint_as_float(cg[x] & 0xffff0000u), p0 = __uint_as_float(pg[x] << 16), p1 = __uint_as_float(pg[x] & 0xffff0000u);
;                 const float ma = x < 2 ? m0[2 * x] : m1[2 * x - 4], mb = x < 2 ? m0[2 * x + 1] : m1[2 * x - 3];
;                 og[x] = pk2(sigmoidf_(c0 + ma * (p0 - c0)), sigmoidf_(c1 + mb * (p1 - c1))); }
;             *(u32x4*)(AG + j * 136 + c8) = og; }
	v_lshlrev_b32_e32 v11, 16, v198
	v_lshlrev_b32_e32 v12, 16, v182
	v_and_b32_e32 v182, 0xffff0000, v182
	v_and_b32_e32 v198, 0xffff0000, v198
	v_lshlrev_b32_e32 v13, 16, v199
	v_lshlrev_b32_e32 v24, 16, v183
	v_and_b32_e32 v183, 0xffff0000, v183
	v_and_b32_e32 v199, 0xffff0000, v199
	v_lshlrev_b32_e32 v15, 16, v200
	v_lshlrev_b32_e32 v26, 16, v184
	v_and_b32_e32 v184, 0xffff0000, v184
	v_and_b32_e32 v200, 0xffff0000, v200
	v_lshlrev_b32_e32 v25, 16, v201
	v_lshlrev_b32_e32 v28, 16, v185
	v_and_b32_e32 v185, 0xffff0000, v185
	v_and_b32_e32 v201, 0xffff0000, v201
	v_sub_f32_e32 v198, v198, v182
	v_sub_f32_e32 v11, v11, v12
	v_sub_f32_e32 v199, v199, v183
	v_sub_f32_e32 v13, v13, v24
	v_sub_f32_e32 v200, v200, v184
	v_sub_f32_e32 v15, v15, v26
	v_sub_f32_e32 v201, v201, v185
	v_sub_f32_e32 v25, v25, v28
	v_fmac_f32_e32 v182, v207, v198
	v_fmac_f32_e32 v12, v206, v11
	v_fmac_f32_e32 v183, v209, v199
	v_fmac_f32_e32 v24, v208, v13
	v_fmac_f32_e32 v184, v211, v200
	v_fmac_f32_e32 v26, v210, v15
	v_fmac_f32_e32 v185, v213, v201
	v_fmac_f32_e32 v28, v212, v25
	v_mul_f32_e32 v182, 0xbfb8aa3b, v182
	v_mul_f32_e32 v183, 0xbfb8aa3b, v183
	v_mul_f32_e32 v184, 0xbfb8aa3b, v184
	v_mul_f32_e32 v185, 0xbfb8aa3b, v185
	v_mul_f32_e32 v12, 0xbfb8aa3b, v12
	v_mul_f32_e32 v24, 0xbfb8aa3b, v24
	v_mul_f32_e32 v26, 0xbfb8aa3b, v26
	v_mul_f32_e32 v28, 0xbfb8aa3b, v28
	v_exp_f32_e32 v182, v182
	v_exp_f32_e32 v183, v183
	v_exp_f32_e32 v184, v184
	v_exp_f32_e32 v185, v185
	v_exp_f32_e32 v12, v12
	v_exp_f32_e32 v24, v24
	v_exp_f32_e32 v26, v26
	v_exp_f32_e32 v28, v28
	v_add_f32_e32 v182, 1.0, v182
	v_add_f32_e32 v183, 1.0, v183
	v_add_f32_e32 v184, 1.0, v184
	v_add_f32_e32 v185, 1.0, v185
	v_add_f32_e32 v12, 1.0, v12
	v_add_f32_e32 v24, 1.0, v24
	v_add_f32_e32 v26, 1.0, v26
	v_add_f32_e32 v28, 1.0, v28
	v_rcp_f32_e32 v182, v182
	v_rcp_f32_e32 v183, v183
	v_rcp_f32_e32 v184, v184
	v_rcp_f32_e32 v185, v185
	v_rcp_f32_e32 v12, v12
	v_rcp_f32_e32 v24, v24
	v_rcp_f32_e32 v26, v26
	v_rcp_f32_e32 v28, v28
	s_nop 0
	v_cvt_pk_bf16_f32 v182, v12, v182
	v_cvt_pk_bf16_f32 v183, v24, v183
	v_cvt_pk_bf16_f32 v184, v26, v184
	v_cvt_pk_bf16_f32 v185, v28, v185
	ds_write_b128 v153, v[182:185] offset:45056
	s_waitcnt vmcnt(0)
	v_lshlrev_b32_e32 v11, 16, v202
	v_lshlrev_b32_e32 v12, 16, v186
	v_and_b32_e32 v186, 0xffff0000, v186
	v_and_b32_e32 v202, 0xffff0000, v202
	v_lshlrev_b32_e32 v13, 16, v203
	v_lshlrev_b32_e32 v24, 16, v187
	v_and_b32_e32 v187, 0xffff0000, v187
	v_and_b32_e32 v203, 0xffff0000, v203
	v_lshlrev_b32_e32 v15, 16, v204
	v_lshlrev_b32_e32 v26, 16, v188
	v_and_b32_e32 v188, 0xffff0000, v188
	v_and_b32_e32 v204, 0xffff0000, v204
	v_lshlrev_b32_e32 v25, 16, v205
	v_lshlrev_b32_e32 v28, 16, v189
	v_and_b32_e32 v189, 0xffff0000, v189
	v_and_b32_e32 v205, 0xffff0000, v205
	v_sub_f32_e32 v202, v202, v186
	v_sub_f32_e32 v11, v11, v12
	v_sub_f32_e32 v203, v203, v187
	v_sub_f32_e32 v13, v13, v24
	v_sub_f32_e32 v204, v204, v188
	v_sub_f32_e32 v15, v15, v26
	v_sub_f32_e32 v205, v205, v189
	v_sub_f32_e32 v25, v25, v28
	v_fmac_f32_e32 v186, v207, v202
	v_fmac_f32_e32 v12, v206, v11
	v_fmac_f32_e32 v187, v209, v203
	v_fmac_f32_e32 v24, v208, v13
	v_fmac_f32_e32 v188, v211, v204
	v_fmac_f32_e32 v26, v210, v15
	v_fmac_f32_e32 v189, v213, v205
	v_fmac_f32_e32 v28, v212, v25
	v_mul_f32_e32 v186, 0xbfb8aa3b, v186
	v_mul_f32_e32 v187, 0xbfb8aa3b, v187
	v_mul_f32_e32 v188, 0xbfb8aa3b, v188
	v_mul_f32_e32 v189, 0xbfb8aa3b, v189
	v_mul_f32_e32 v12, 0xbfb8aa3b, v12
	v_mul_f32_e32 v24, 0xbfb8aa3b, v24
	v_mul_f32_e32 v26, 0xbfb8aa3b, v26
	v_mul_f32_e32 v28, 0xbfb8aa3b, v28
	v_exp_f32_e32 v186, v186
	v_exp_f32_e32 v187, v187
	v_exp_f32_e32 v188, v188
	v_exp_f32_e32 v189, v189
	v_exp_f32_e32 v12, v12
	v_exp_f32_e32 v24, v24
	v_exp_f32_e32 v26, v26
	v_exp_f32_e32 v28, v28
	v_add_f32_e32 v186, 1.0, v186
	v_add_f32_e32 v187, 1.0, v187
	v_add_f32_e32 v188, 1.0, v188
	v_add_f32_e32 v189, 1.0, v189
	v_add_f32_e32 v12, 1.0, v12
	v_add_f32_e32 v24, 1.0, v24
	v_add_f32_e32 v26, 1.0, v26
	v_add_f32_e32 v28, 1.0, v28
	v_rcp_f32_e32 v186, v186
	v_rcp_f32_e32 v187, v187
	v_rcp_f32_e32 v188, v188
	v_rcp_f32_e32 v189, v189
	v_rcp_f32_e32 v12, v12
	v_rcp_f32_e32 v24, v24
	v_rcp_f32_e32 v26, v26
	v_rcp_f32_e32 v28, v28
	s_nop 0
	v_cvt_pk_bf16_f32 v186, v12, v186
	v_cvt_pk_bf16_f32 v187, v24, v187
	v_cvt_pk_bf16_f32 v188, v26, v188
	v_cvt_pk_bf16_f32 v189, v28, v189
	ds_write_b128 v153, v[186:189] offset:53760
	s_movk_i32 s41, 0x1ff
	s_branch .LBB0_641
